# la + P4 forget-gate bias loaded once before the row loops (removes a per-row global load and vmcnt(0) drain)
# speedup vs baseline: 1.0260x; 1.0057x over previous
.LBB0_397:
	s_or_b64 exec, exec, s[0:1]
	s_andn2_b64 vcc, exec, s[10:11]
	s_waitcnt lgkmcnt(0)
	s_barrier
	s_cbranch_vccnz .LBB0_406
	v_mbcnt_hi_u32_b32 v2, -1, v208
	v_and_b32_e32 v3, 64, v2
	v_add_u32_e32 v3, 64, v3
	v_xor_b32_e32 v4, 1, v2
	v_cmp_lt_i32_e32 vcc, v4, v3
	v_and_b32_e32 v131, 63, v0
	v_mov_b32_e32 v129, 0
	v_cndmask_b32_e32 v4, v2, v4, vcc
	v_lshlrev_b32_e32 v209, 2, v4
	v_xor_b32_e32 v4, 2, v2
	v_cmp_lt_i32_e32 vcc, v4, v3
	v_lshlrev_b32_e32 v0, 4, v131
	v_mov_b32_e32 v1, v129
	v_cndmask_b32_e32 v4, v2, v4, vcc
	v_lshlrev_b32_e32 v211, 2, v4
	v_xor_b32_e32 v4, 4, v2
	v_cmp_lt_i32_e32 vcc, v4, v3
	v_add_u32_e32 v124, 0, v0
	v_lshl_add_u64 v[176:177], s[62:63], 0, v[0:1]
	v_cndmask_b32_e32 v4, v2, v4, vcc
	v_lshlrev_b32_e32 v212, 2, v4
	v_xor_b32_e32 v4, 8, v2
	v_cmp_lt_i32_e32 vcc, v4, v3
	v_lshl_add_u64 v[180:181], s[22:23], 0, v[0:1]
	s_ashr_i32 s21, s20, 31
	v_cndmask_b32_e32 v4, v2, v4, vcc
	v_lshlrev_b32_e32 v213, 2, v4
	v_xor_b32_e32 v4, 16, v2
	v_cmp_lt_i32_e32 vcc, v4, v3
	s_lshl_b64 s[0:1], s[20:21], 5
	s_add_u32 s0, s66, s0
	v_cndmask_b32_e32 v4, v2, v4, vcc
	v_lshlrev_b32_e32 v214, 2, v4
	v_xor_b32_e32 v4, 32, v2
	v_cmp_lt_i32_e32 vcc, v4, v3
	v_lshlrev_b32_e32 v128, 2, v131
	s_addc_u32 s1, s67, s1
	v_cndmask_b32_e32 v2, v2, v4, vcc
	v_lshlrev_b32_e32 v215, 2, v2
	ds_read_b128 v[0:3], v124
	ds_read_b128 v[4:7], v124 offset:1024
	ds_read_b128 v[8:11], v124 offset:2048
	ds_read_b128 v[12:15], v124 offset:3072
	ds_read_b128 v[16:19], v124 offset:4096
	ds_read_b128 v[20:23], v124 offset:5120
	ds_read_b128 v[24:27], v124 offset:6144
	ds_read_b128 v[28:31], v124 offset:7168
	ds_read_b128 v[32:35], v124 offset:8192
	ds_read_b128 v[36:39], v124 offset:9216
	ds_read_b128 v[40:43], v124 offset:10240
	ds_read_b128 v[44:47], v124 offset:11264
	ds_read_b128 v[48:51], v124 offset:12288
	ds_read_b128 v[52:55], v124 offset:13312
	ds_read_b128 v[56:59], v124 offset:14336
	ds_read_b128 v[60:63], v124 offset:15360
	ds_read_b128 v[64:67], v124 offset:16384
	ds_read_b128 v[68:71], v124 offset:17408
	ds_read_b128 v[72:75], v124 offset:18432
	ds_read_b128 v[76:79], v124 offset:19456
	ds_read_b128 v[80:83], v124 offset:20480
	ds_read_b128 v[84:87], v124 offset:21504
	ds_read_b128 v[88:91], v124 offset:22528
	ds_read_b128 v[92:95], v124 offset:23552
	ds_read_b128 v[96:99], v124 offset:24576
	ds_read_b128 v[100:103], v124 offset:25600
	ds_read_b128 v[104:107], v124 offset:26624
	ds_read_b128 v[108:111], v124 offset:27648
	ds_read_b128 v[112:115], v124 offset:28672
	ds_read_b128 v[116:119], v124 offset:29696
	ds_read_b128 v[120:123], v124 offset:30720
	ds_read_b128 v[124:127], v124 offset:31744
	v_lshl_add_u64 v[136:137], s[0:1], 0, v[128:129]
	s_mov_b64 s[0:1], 0x500000
	s_ashr_i32 s25, s24, 31
	v_lshl_add_u64 v[182:183], v[136:137], 0, s[0:1]
	s_lshl_b64 s[22:23], s[24:25], 5
	s_lshl_b64 s[0:1], s[20:21], 11
	s_add_u32 s0, s66, s0
	v_lshlrev_b32_e32 v136, 3, v131
	v_mov_b32_e32 v137, v129
	s_addc_u32 s1, s67, s1
	v_or_b32_e32 v130, 0x100, v128
	v_or_b32_e32 v132, 0x200, v128
	v_or_b32_e32 v134, 0x300, v128
	v_lshl_add_u64 v[136:137], s[0:1], 0, v[136:137]
	s_mov_b64 s[0:1], 0x4000400
	v_cmp_gt_u32_e64 s[4:5], 8, v131
	v_lshl_add_u64 v[178:179], s[42:43], 0, v[128:129]
	v_cmp_eq_u32_e64 s[6:7], 7, v131
	v_cmp_eq_u32_e64 s[8:9], 6, v131
	v_cmp_eq_u32_e64 s[10:11], 5, v131
	v_cmp_eq_u32_e64 s[12:13], 4, v131
	v_cmp_eq_u32_e64 s[14:15], 3, v131
	v_cmp_eq_u32_e64 s[16:17], 2, v131
	v_cmp_eq_u32_e64 s[18:19], 1, v131
	v_lshl_add_u64 v[184:185], v[136:137], 0, s[0:1]
	s_lshl_b64 s[26:27], s[24:25], 11
	v_lshlrev_b32_e32 v216, 2, v128
	v_lshlrev_b32_e32 v217, 2, v130
	v_lshlrev_b32_e32 v218, 2, v132
	v_lshlrev_b32_e32 v219, 2, v134
	v_mov_b32_e32 v220, 0x358637bd
	s_mov_b32 s25, 0xf800000
	v_mov_b32_e32 v221, 0x260
	s_movk_i32 s42, 0x7fff
	s_mov_b32 s43, 0xffff0000
	s_mov_b32 s48, 0xbfb8aa3b
	s_mov_b32 s49, 0x800000
	s_mov_b32 s52, 0x3f317217
	s_mov_b32 s53, 0x7f800000
	s_mov_b64 s[28:29], 0x4000
	s_mov_b64 s[100:101], 0x100
	v_mov_b32_e32 v222, 0x41b17218
	s_and_saveexec_b64 s[98:99], s[4:5]
	global_load_dword v255, v[178:179], off
	s_mov_b64 exec, s[98:99]
	s_branch .LBB0_400

.LBB0_404:
	v_mul_f32_e32 v206, v173, v173
	v_mul_f32_e32 v207, v175, v175
	v_fmac_f32_e32 v206, v172, v172
	v_fmac_f32_e32 v207, v174, v174
	v_add_f32_e32 v206, v206, v207
	v_mul_f32_e32 v207, v169, v169
	v_mul_f32_e32 v223, v171, v171
	v_fmac_f32_e32 v207, v168, v168
	v_fmac_f32_e32 v223, v170, v170
	v_add_f32_e32 v207, v207, v223
	v_add_f32_e32 v206, v207, v206
	v_mul_f32_e32 v207, v165, v165
	v_mul_f32_e32 v223, v167, v167
	v_fmac_f32_e32 v207, v164, v164
	v_fmac_f32_e32 v223, v166, v166
	v_add_f32_e32 v207, v207, v223
	v_add_f32_e32 v206, v207, v206
	v_mul_f32_e32 v207, v161, v161
	v_mul_f32_e32 v223, v163, v163
	v_fmac_f32_e32 v207, v160, v160
	v_fmac_f32_e32 v223, v162, v162
	v_add_f32_e32 v207, v207, v223
	v_add_f32_e32 v206, v207, v206
	ds_bpermute_b32 v207, v209, v206
	s_waitcnt lgkmcnt(0)
	v_add_f32_e32 v206, v206, v207
	ds_bpermute_b32 v207, v211, v206
	s_waitcnt lgkmcnt(0)
	v_add_f32_e32 v206, v206, v207
	ds_bpermute_b32 v207, v212, v206
	s_waitcnt lgkmcnt(0)
	v_add_f32_e32 v206, v206, v207
	ds_bpermute_b32 v207, v213, v206
	s_waitcnt lgkmcnt(0)
	v_add_f32_e32 v206, v206, v207
	ds_bpermute_b32 v207, v214, v206
	s_waitcnt lgkmcnt(0)
	v_add_f32_e32 v206, v206, v207
	ds_bpermute_b32 v207, v215, v206
	s_waitcnt lgkmcnt(0)
	v_add_f32_e32 v206, v206, v207
	v_fmamk_f32 v206, v206, 0x3a800000, v220
	v_mul_f32_e32 v207, 0x4f800000, v206
	v_cmp_gt_f32_e32 vcc, s25, v206
	s_nop 1
	v_cndmask_b32_e32 v206, v206, v207, vcc
	v_sqrt_f32_e32 v207, v206
	s_nop 0
	v_add_u32_e32 v223, -1, v207
	v_add_u32_e32 v224, 1, v207
	v_fma_f32 v225, -v223, v207, v206
	v_fma_f32 v226, -v224, v207, v206
	v_cmp_ge_f32_e64 s[0:1], 0, v225
	s_nop 1
	v_cndmask_b32_e64 v207, v207, v223, s[0:1]
	v_cmp_lt_f32_e64 s[0:1], 0, v226
	s_nop 1
	v_cndmask_b32_e64 v207, v207, v224, s[0:1]
	v_mul_f32_e32 v223, 0x37800000, v207
	v_cndmask_b32_e32 v207, v207, v223, vcc
	v_cmp_class_f32_e32 vcc, v206, v221
	s_nop 1
	v_cndmask_b32_e32 v206, v207, v206, vcc
	v_div_scale_f32 v207, s[0:1], v206, v206, 1.0
	v_rcp_f32_e32 v223, v207
	v_div_scale_f32 v224, vcc, 1.0, v206, 1.0
	v_fma_f32 v225, -v207, v223, 1.0
	v_fmac_f32_e32 v223, v225, v223
	v_mul_f32_e32 v225, v224, v223
	v_fma_f32 v226, -v207, v225, v224
	v_fmac_f32_e32 v225, v226, v223
	v_fma_f32 v207, -v207, v225, v224
	v_div_fmas_f32 v207, v207, v223, v225
	v_div_fixup_f32 v206, v207, v206, 1.0
	v_pk_mul_f32 v[224:225], v[172:173], v[206:207] op_sel_hi:[1,0]
	v_pk_mul_f32 v[172:173], v[174:175], v[206:207] op_sel_hi:[1,0]
	v_pk_fma_f32 v[174:175], v[192:193], v[224:225], v[128:129]
	v_pk_fma_f32 v[172:173], v[190:191], v[172:173], v[130:131]
	v_bfe_u32 v207, v174, 16, 1
	v_bfe_u32 v223, v175, 16, 1
	v_add3_u32 v207, v174, v207, s42
	v_lshrrev_b32_e32 v207, 16, v207
	v_add3_u32 v223, v175, v223, s42
	v_and_or_b32 v224, v223, s43, v207
	v_bfe_u32 v207, v172, 16, 1
	v_add3_u32 v207, v172, v207, s42
	v_bfe_u32 v223, v173, 16, 1
	v_lshrrev_b32_e32 v207, 16, v207
	v_add3_u32 v223, v173, v223, s42
	v_and_or_b32 v225, v223, s43, v207
	global_store_dwordx2 v[186:187], v[224:225], off offset:-1024
	v_pk_mul_f32 v[224:225], v[168:169], v[206:207] op_sel_hi:[1,0]
	v_pk_mul_f32 v[168:169], v[170:171], v[206:207] op_sel_hi:[1,0]
	v_pk_fma_f32 v[170:171], v[196:197], v[224:225], v[132:133]
	v_pk_fma_f32 v[168:169], v[194:195], v[168:169], v[134:135]
	v_bfe_u32 v207, v170, 16, 1
	v_add3_u32 v207, v170, v207, s42
	v_bfe_u32 v223, v171, 16, 1
	v_lshrrev_b32_e32 v207, 16, v207
	v_add3_u32 v223, v171, v223, s42
	v_and_or_b32 v224, v223, s43, v207
	v_bfe_u32 v207, v168, 16, 1
	v_add3_u32 v207, v168, v207, s42
	v_bfe_u32 v223, v169, 16, 1
	v_lshrrev_b32_e32 v207, 16, v207
	v_add3_u32 v223, v169, v223, s42
	v_and_or_b32 v225, v223, s43, v207
	global_store_dwordx2 v[186:187], v[224:225], off offset:-512
	v_pk_mul_f32 v[224:225], v[164:165], v[206:207] op_sel_hi:[1,0]
	v_pk_mul_f32 v[164:165], v[166:167], v[206:207] op_sel_hi:[1,0]
	s_waitcnt vmcnt(3)
	v_pk_fma_f32 v[166:167], v[200:201], v[224:225], v[136:137]
	v_pk_fma_f32 v[164:165], v[198:199], v[164:165], v[138:139]
	v_bfe_u32 v207, v166, 16, 1
	v_add3_u32 v207, v166, v207, s42
	v_bfe_u32 v223, v167, 16, 1
	v_lshrrev_b32_e32 v207, 16, v207
	v_add3_u32 v223, v167, v223, s42
	v_and_or_b32 v224, v223, s43, v207
	v_bfe_u32 v207, v164, 16, 1
	v_add3_u32 v207, v164, v207, s42
	v_bfe_u32 v223, v165, 16, 1
	v_lshrrev_b32_e32 v207, 16, v207
	v_add3_u32 v223, v165, v223, s42
	v_and_or_b32 v225, v223, s43, v207
	v_pk_mul_f32 v[226:227], v[160:161], v[206:207] op_sel_hi:[1,0]
	v_pk_mul_f32 v[160:161], v[162:163], v[206:207] op_sel_hi:[1,0]
	v_mul_f32_e32 v206, v1, v175
	v_mul_f32_e32 v207, v3, v173
	v_fmac_f32_e32 v206, v0, v174
	v_fmac_f32_e32 v207, v2, v172
	v_add_f32_e32 v206, v206, v207
	v_mul_f32_e32 v207, v5, v171
	v_mul_f32_e32 v223, v7, v169
	v_fmac_f32_e32 v207, v4, v170
	v_fmac_f32_e32 v223, v6, v168
	v_add_f32_e32 v206, 0, v206
	v_add_f32_e32 v207, v207, v223
	v_add_f32_e32 v206, v207, v206
	v_mul_f32_e32 v207, v9, v167
	v_mul_f32_e32 v223, v11, v165
	v_fmac_f32_e32 v207, v8, v166
	v_fmac_f32_e32 v223, v10, v164
	s_waitcnt vmcnt(2)
	v_pk_fma_f32 v[160:161], v[202:203], v[160:161], v[142:143]
	v_pk_fma_f32 v[162:163], v[204:205], v[226:227], v[140:141]
	v_add_f32_e32 v207, v207, v223
	v_add_f32_e32 v206, v207, v206
	v_mul_f32_e32 v207, v13, v163
	v_mul_f32_e32 v223, v15, v161
	v_fmac_f32_e32 v207, v12, v162
	v_fmac_f32_e32 v223, v14, v160
	v_add_f32_e32 v207, v207, v223
	v_mul_f32_e32 v223, v175, v17
	v_mul_f32_e32 v226, v173, v19
	v_fmac_f32_e32 v223, v174, v16
	v_fmac_f32_e32 v226, v172, v18
	v_add_f32_e32 v223, v223, v226
	v_mul_f32_e32 v226, v171, v21
	v_mul_f32_e32 v227, v169, v23
	v_fmac_f32_e32 v226, v170, v20
	v_fmac_f32_e32 v227, v168, v22
	v_add_f32_e32 v223, 0, v223
	v_add_f32_e32 v226, v226, v227
	v_add_f32_e32 v223, v223, v226
	v_mul_f32_e32 v226, v167, v25
	v_mul_f32_e32 v227, v165, v27
	v_fmac_f32_e32 v226, v166, v24
	v_fmac_f32_e32 v227, v164, v26
	v_add_f32_e32 v226, v226, v227
	v_add_f32_e32 v223, v223, v226
	v_mul_f32_e32 v226, v163, v29
	v_mul_f32_e32 v227, v161, v31
	v_fmac_f32_e32 v226, v162, v28
	v_fmac_f32_e32 v227, v160, v30
	v_add_f32_e32 v226, v226, v227
	v_add_f32_e32 v206, v207, v206
	v_add_f32_e32 v223, v223, v226
	ds_bpermute_b32 v207, v209, v206
	ds_bpermute_b32 v226, v209, v223
	global_store_dwordx2 v[186:187], v[224:225], off
	v_bfe_u32 v224, v162, 16, 1
	v_add3_u32 v224, v162, v224, s42
	s_waitcnt lgkmcnt(1)
	v_add_f32_e32 v206, v206, v207
	s_waitcnt lgkmcnt(0)
	v_add_f32_e32 v223, v223, v226
	ds_bpermute_b32 v207, v211, v206
	ds_bpermute_b32 v225, v211, v223
	v_bfe_u32 v226, v163, 16, 1
	v_lshrrev_b32_e32 v224, 16, v224
	v_add3_u32 v226, v163, v226, s42
	s_waitcnt lgkmcnt(1)
	v_add_f32_e32 v206, v206, v207
	s_waitcnt lgkmcnt(0)
	v_add_f32_e32 v223, v223, v225
	ds_bpermute_b32 v207, v212, v206
	ds_bpermute_b32 v225, v212, v223
	v_mul_f32_e32 v228, v169, v39
	v_fmac_f32_e32 v228, v168, v38
	v_mul_f32_e32 v229, v173, v51
	s_waitcnt lgkmcnt(1)
	v_add_f32_e32 v207, v206, v207
	s_waitcnt lgkmcnt(0)
	v_add_f32_e32 v223, v223, v225
	ds_bpermute_b32 v227, v213, v207
	ds_bpermute_b32 v225, v213, v223
	v_and_or_b32 v206, v226, s43, v224
	v_bfe_u32 v224, v160, 16, 1
	v_fmac_f32_e32 v229, v172, v50
	s_waitcnt lgkmcnt(1)
	v_add_f32_e32 v207, v207, v227
	s_waitcnt lgkmcnt(0)
	v_add_f32_e32 v225, v223, v225
	ds_bpermute_b32 v226, v214, v207
	ds_bpermute_b32 v227, v214, v225
	v_add3_u32 v223, v160, v224, s42
	v_lshrrev_b32_e32 v233, 16, v223
	v_mul_f32_e32 v230, v169, v55
	s_waitcnt lgkmcnt(1)
	v_add_f32_e32 v223, v207, v226
	s_waitcnt lgkmcnt(0)
	v_add_f32_e32 v225, v225, v227
	v_mul_f32_e32 v207, v175, v33
	v_mul_f32_e32 v227, v173, v35
	v_fmac_f32_e32 v207, v174, v32
	v_fmac_f32_e32 v227, v172, v34
	v_add_f32_e32 v207, v207, v227
	v_mul_f32_e32 v227, v171, v37
	v_fmac_f32_e32 v227, v170, v36
	v_add_f32_e32 v207, 0, v207
	v_add_f32_e32 v227, v227, v228
	v_add_f32_e32 v207, v207, v227
	v_mul_f32_e32 v227, v167, v41
	v_mul_f32_e32 v228, v165, v43
	v_fmac_f32_e32 v227, v166, v40
	v_fmac_f32_e32 v228, v164, v42
	v_add_f32_e32 v227, v227, v228
	v_add_f32_e32 v207, v207, v227
	v_mul_f32_e32 v227, v163, v45
	v_mul_f32_e32 v228, v161, v47
	v_fmac_f32_e32 v227, v162, v44
	v_fmac_f32_e32 v228, v160, v46
	v_add_f32_e32 v227, v227, v228
	v_mul_f32_e32 v228, v175, v49
	v_fmac_f32_e32 v228, v174, v48
	v_add_f32_e32 v228, v228, v229
	v_mul_f32_e32 v229, v171, v53
	v_fmac_f32_e32 v229, v170, v52
	v_fmac_f32_e32 v230, v168, v54
	v_add_f32_e32 v228, 0, v228
	v_add_f32_e32 v229, v229, v230
	v_add_f32_e32 v228, v228, v229
	v_mul_f32_e32 v229, v167, v57
	v_mul_f32_e32 v230, v165, v59
	v_fmac_f32_e32 v229, v166, v56
	v_fmac_f32_e32 v230, v164, v58
	v_add_f32_e32 v229, v229, v230
	v_add_f32_e32 v228, v228, v229
	v_mul_f32_e32 v229, v163, v61
	v_mul_f32_e32 v230, v161, v63
	v_fmac_f32_e32 v229, v162, v60
	v_fmac_f32_e32 v230, v160, v62
	v_add_f32_e32 v229, v229, v230
	v_mul_f32_e32 v230, v175, v65
	v_mul_f32_e32 v231, v173, v67
	v_fmac_f32_e32 v230, v174, v64
	v_fmac_f32_e32 v231, v172, v66
	v_add_f32_e32 v230, v230, v231
	v_mul_f32_e32 v231, v171, v69
	v_mul_f32_e32 v232, v169, v71
	v_fmac_f32_e32 v231, v170, v68
	v_fmac_f32_e32 v232, v168, v70
	v_add_f32_e32 v230, 0, v230
	v_add_f32_e32 v231, v231, v232
	v_add_f32_e32 v230, v230, v231
	v_mul_f32_e32 v231, v167, v73
	v_mul_f32_e32 v232, v165, v75
	v_fmac_f32_e32 v231, v166, v72
	v_fmac_f32_e32 v232, v164, v74
	v_add_f32_e32 v231, v231, v232
	v_add_f32_e32 v230, v230, v231
	v_mul_f32_e32 v231, v163, v77
	v_mul_f32_e32 v232, v161, v79
	v_fmac_f32_e32 v231, v162, v76
	v_fmac_f32_e32 v232, v160, v78
	v_add_f32_e32 v231, v231, v232
	v_add_f32_e32 v207, v207, v227
	v_add_f32_e32 v230, v230, v231
	ds_bpermute_b32 v227, v209, v207
	ds_bpermute_b32 v231, v209, v230
	v_mul_f32_e32 v235, v169, v87
	v_fmac_f32_e32 v235, v168, v86
	v_mul_f32_e32 v236, v173, v99
	s_waitcnt lgkmcnt(1)
	v_add_f32_e32 v207, v207, v227
	s_waitcnt lgkmcnt(0)
	v_add_f32_e32 v230, v230, v231
	ds_bpermute_b32 v227, v211, v207
	ds_bpermute_b32 v231, v211, v230
	v_fmac_f32_e32 v236, v172, v98
	v_mul_f32_e32 v237, v169, v103
	v_fmac_f32_e32 v237, v168, v102
	s_waitcnt lgkmcnt(1)
	v_add_f32_e32 v207, v207, v227
	s_waitcnt lgkmcnt(0)
	v_add_f32_e32 v230, v230, v231
	ds_bpermute_b32 v227, v212, v207
	ds_bpermute_b32 v231, v212, v230
	v_mul_f32_e32 v169, v169, v119
	v_fmac_f32_e32 v169, v168, v118
	v_add_f32_e32 v228, v228, v229
	s_waitcnt lgkmcnt(1)
	v_add_f32_e32 v207, v207, v227
	s_waitcnt lgkmcnt(0)
	v_add_f32_e32 v230, v230, v231
	ds_bpermute_b32 v227, v213, v207
	ds_bpermute_b32 v231, v213, v230
	ds_bpermute_b32 v229, v209, v228
	ds_bpermute_b32 v224, v215, v223
	ds_bpermute_b32 v226, v215, v225
	s_waitcnt lgkmcnt(4)
	v_add_f32_e32 v207, v207, v227
	s_waitcnt lgkmcnt(3)
	v_add_f32_e32 v231, v230, v231
	ds_bpermute_b32 v227, v214, v207
	ds_bpermute_b32 v234, v214, v231
	s_waitcnt lgkmcnt(4)
	v_add_f32_e32 v228, v228, v229
	ds_bpermute_b32 v229, v211, v228
	s_waitcnt lgkmcnt(2)
	v_add_f32_e32 v227, v207, v227
	s_waitcnt lgkmcnt(1)
	v_add_f32_e32 v231, v231, v234
	v_mul_f32_e32 v207, v175, v81
	v_mul_f32_e32 v234, v173, v83
	v_fmac_f32_e32 v207, v174, v80
	v_fmac_f32_e32 v234, v172, v82
	v_add_f32_e32 v207, v207, v234
	v_mul_f32_e32 v234, v171, v85
	v_fmac_f32_e32 v234, v170, v84
	v_add_f32_e32 v207, 0, v207
	v_add_f32_e32 v234, v234, v235
	v_add_f32_e32 v207, v207, v234
	v_mul_f32_e32 v234, v167, v89
	v_mul_f32_e32 v235, v165, v91
	v_fmac_f32_e32 v234, v166, v88
	v_fmac_f32_e32 v235, v164, v90
	v_add_f32_e32 v234, v234, v235
	v_add_f32_e32 v207, v207, v234
	v_mul_f32_e32 v234, v163, v93
	v_mul_f32_e32 v235, v161, v95
	v_fmac_f32_e32 v234, v162, v92
	v_fmac_f32_e32 v235, v160, v94
	v_add_f32_e32 v234, v234, v235
	v_mul_f32_e32 v235, v175, v97
	v_fmac_f32_e32 v235, v174, v96
	v_add_f32_e32 v235, v235, v236
	v_mul_f32_e32 v236, v171, v101
	v_fmac_f32_e32 v236, v170, v100
	v_add_f32_e32 v235, 0, v235
	v_add_f32_e32 v236, v236, v237
	v_add_f32_e32 v235, v235, v236
	v_mul_f32_e32 v236, v167, v105
	v_mul_f32_e32 v237, v165, v107
	v_fmac_f32_e32 v236, v166, v104
	v_fmac_f32_e32 v237, v164, v106
	v_mul_f32_e32 v175, v175, v113
	v_mul_f32_e32 v173, v173, v115
	v_add_f32_e32 v236, v236, v237
	v_fmac_f32_e32 v175, v174, v112
	v_fmac_f32_e32 v173, v172, v114
	v_mul_f32_e32 v171, v171, v117
	v_add_f32_e32 v235, v235, v236
	v_mul_f32_e32 v236, v163, v109
	v_add_f32_e32 v172, v175, v173
	v_fmac_f32_e32 v171, v170, v116
	v_mul_f32_e32 v167, v167, v121
	v_mul_f32_e32 v165, v165, v123
	v_mul_f32_e32 v163, v163, v125
	v_fmac_f32_e32 v236, v162, v108
	v_mul_f32_e32 v237, v161, v111
	v_add_f32_e32 v172, 0, v172
	v_add_f32_e32 v168, v171, v169
	v_fmac_f32_e32 v167, v166, v120
	v_fmac_f32_e32 v165, v164, v122
	v_fmac_f32_e32 v163, v162, v124
	v_mul_f32_e32 v162, v161, v127
	v_fmac_f32_e32 v237, v160, v110
	v_add_f32_e32 v168, v172, v168
	v_add_f32_e32 v164, v167, v165
	v_fmac_f32_e32 v162, v160, v126
	v_add_f32_e32 v236, v236, v237
	v_add_f32_e32 v164, v168, v164
	v_add_f32_e32 v160, v163, v162
	v_add_f32_e32 v207, v207, v234
	v_add_f32_e32 v235, v235, v236
	v_add_f32_e32 v160, v164, v160
	ds_bpermute_b32 v234, v209, v207
	ds_bpermute_b32 v236, v209, v235
	ds_bpermute_b32 v162, v209, v160
	s_waitcnt lgkmcnt(3)
	v_add_f32_e32 v228, v228, v229
	ds_bpermute_b32 v229, v212, v228
	s_waitcnt lgkmcnt(3)
	v_add_f32_e32 v163, v207, v234
	s_waitcnt lgkmcnt(2)
	v_add_f32_e32 v165, v235, v236
	s_waitcnt lgkmcnt(1)
	v_add_f32_e32 v160, v160, v162
	ds_bpermute_b32 v164, v211, v163
	ds_bpermute_b32 v166, v211, v165
	ds_bpermute_b32 v162, v211, v160
	s_waitcnt lgkmcnt(3)
	v_add_f32_e32 v228, v228, v229
	ds_bpermute_b32 v229, v213, v228
	s_waitcnt lgkmcnt(3)
	v_add_f32_e32 v163, v163, v164
	s_waitcnt lgkmcnt(2)
	v_add_f32_e32 v165, v165, v166
	s_waitcnt lgkmcnt(1)
	v_add_f32_e32 v160, v160, v162
	ds_bpermute_b32 v164, v212, v163
	ds_bpermute_b32 v166, v212, v165
	ds_bpermute_b32 v162, v212, v160
	s_waitcnt lgkmcnt(3)
	v_add_f32_e32 v229, v228, v229
	ds_bpermute_b32 v232, v214, v229
	s_waitcnt lgkmcnt(3)
	v_add_f32_e32 v163, v163, v164
	s_waitcnt lgkmcnt(2)
	v_add_f32_e32 v165, v165, v166
	s_waitcnt lgkmcnt(1)
	v_add_f32_e32 v160, v160, v162
	ds_bpermute_b32 v164, v213, v163
	ds_bpermute_b32 v166, v213, v165
	ds_bpermute_b32 v162, v213, v160
	s_waitcnt lgkmcnt(3)
	v_add_f32_e32 v229, v229, v232
	ds_bpermute_b32 v228, v215, v227
	s_waitcnt lgkmcnt(3)
	v_add_f32_e32 v163, v163, v164
	s_waitcnt lgkmcnt(2)
	v_add_f32_e32 v165, v165, v166
	s_waitcnt lgkmcnt(1)
	v_add_f32_e32 v167, v160, v162
	ds_bpermute_b32 v164, v214, v163
	ds_bpermute_b32 v166, v214, v165
	ds_bpermute_b32 v168, v214, v167
	ds_bpermute_b32 v230, v215, v229
	ds_bpermute_b32 v232, v215, v231
	s_waitcnt lgkmcnt(4)
	v_add_f32_e32 v160, v163, v164
	s_waitcnt lgkmcnt(3)
	v_add_f32_e32 v163, v165, v166
	s_waitcnt lgkmcnt(2)
	v_add_f32_e32 v165, v167, v168
	ds_bpermute_b32 v162, v215, v160
	ds_bpermute_b32 v164, v215, v163
	ds_bpermute_b32 v166, v215, v165
	v_bfe_u32 v167, v161, 16, 1
	v_add3_u32 v161, v161, v167, s42
	v_and_or_b32 v207, v161, s43, v233
	global_store_dwordx2 v[186:187], v[206:207], off offset:512
	s_and_saveexec_b64 s[36:37], s[4:5]
	s_cbranch_execz .LBB0_401
	v_mov_b32_e32 v161, v255
	v_add_f32_e32 v167, v225, v226
	v_add_f32_e32 v168, v223, v224
	s_waitcnt lgkmcnt(0)
	v_add_f32_e32 v165, v165, v166
	v_add_f32_e32 v166, v227, v228
	v_cndmask_b32_e64 v167, v168, v167, s[18:19]
	v_add_f32_e32 v163, v163, v164
	v_add_f32_e32 v164, v229, v230
	v_cndmask_b32_e64 v166, v167, v166, s[16:17]
	v_add_f32_e32 v160, v160, v162
	v_add_f32_e32 v162, v231, v232
	v_cndmask_b32_e64 v164, v166, v164, s[14:15]
	v_cndmask_b32_e64 v162, v164, v162, s[12:13]
	v_cndmask_b32_e64 v160, v162, v160, s[10:11]
	v_cndmask_b32_e64 v160, v160, v163, s[8:9]
	v_cndmask_b32_e64 v160, v160, v165, s[6:7]
	v_add_f32_e32 v160, v160, v161
	v_mul_f32_e64 v161, |v160|, s48
	v_exp_f32_e32 v161, v161
	v_min_f32_e32 v160, 0, v160
	v_add_f32_e32 v161, 1.0, v161
	v_cmp_gt_f32_e32 vcc, s49, v161
	s_nop 1
	v_cndmask_b32_e64 v162, 0, 32, vcc
	v_ldexp_f32 v161, v161, v162
	v_log_f32_e32 v161, v161
	s_nop 0
	v_mul_f32_e32 v162, 0x3f317217, v161
	v_fma_f32 v162, v161, s52, -v162
	v_fmac_f32_e32 v162, 0x3377d1cf, v161
	v_fmac_f32_e32 v162, 0x3f317217, v161
	v_cmp_lt_f32_e64 s[0:1], |v161|, s53
	s_nop 1
	v_cndmask_b32_e64 v161, v161, v162, s[0:1]
	v_cndmask_b32_e32 v162, 0, v222, vcc
	v_sub_f32_e32 v161, v161, v162
	v_sub_f32_e32 v160, v160, v161
	global_store_dword v[188:189], v160, off
	s_branch .LBB0_401
